# v74 + build_rstd_tables row-panel list in closed form for grid 256 (generic walk kept for other grids)
# baseline (speedup 1.0000x reference)
; __device__ __forceinline__ int mk_lane() { int l = (int)__builtin_amdgcn_mbcnt_hi(~0u, __builtin_amdgcn_mbcnt_lo(~0u, 0u)); asm volatile("" : "+v"(l)); return l; }
; #define LAS __attribute__((address_space(3)))
;     __host__ __device__ __forceinline__ bool next(int i, Unit& u) const {
;         const long L = (long)i * G + c; if (L >= nwg) return false;
;         int wgid = (int)L; { const int q = nwg / NXCD, r = nwg % NXCD, xcd = wgid % NXCD, off = wgid / NXCD; wgid = (xcd < r ? xcd * (q + 1) : r * (q + 1) + (xcd - r) * q) + off; }
;         const int nig = WGM * nN, gid = wgid / nig, fm = gid * WGM, gsz = (nM - fm) < WGM ? (nM - fm) : WGM;
;         u.pm = fm + ((wgid % nig) % gsz); u.pn = (wgid % nig) / gsz; if (rev) u.pm = nM - 1 - u.pm; return true;
; template <class Sched> __device__ __forceinline__ void build_rstd_tables(LAS unsigned char* lds, const Sched& S, const float* sspart, float eps, int wave) {
;     const int lane = mk_lane(), tid = wave * 64 + lane;
;     LAS int* pml = (LAS int*)(lds + RING_BYTES + 1536); LAS float* tab = (LAS float*)(lds + RING_BYTES + 2048);
;     if (tid == 0) { int n = 0; pg8::Unit u; for (int i = 0; S.next(i, u); ++i) { bool f = false; for (int j = 0; j < n; ++j) f |= (pml[j] == u.pm); if (!f && n < 8) pml[n++] = u.pm; } pml[8] = n; }
;     __syncthreads();
;     const int n = pml[8];
.LBB0_224:
	s_nop 0
	v_mov_b32_e32 v3, v212
	s_ashr_i32 s20, s82, 31
	v_add_u32_e32 v2, s2, v3
	s_mov_b32 s3, 0
	v_cmp_eq_u32_e32 vcc, 0, v2
	s_and_saveexec_b64 s[44:45], vcc
	s_cbranch_execz .LBB0_246
	s_cmp_lg_u32 s82, 0x100
	s_cbranch_scc1 .Lmy_pmlgen_p2
	s_and_b32 s33, s88, 7
	s_lshl_b32 s33, s33, 4
	s_bfe_u32 s1, s88, 0x30003
	s_add_i32 s33, s33, s1
	v_mov_b32_e32 v0, 0x20600
	v_mov_b32_e32 v1, s33
	ds_write_b32 v0, v1
	v_add_u32_e32 v1, 8, v1
	ds_write_b32 v0, v1 offset:4
	v_mov_b32_e32 v1, 2
	ds_write_b32 v0, v1 offset:32
	s_branch .LBB0_246
.Lmy_pmlgen_p2:
	v_mov_b64_e32 v[0:1], 0x5ff
	s_movk_i32 s21, 0xc1
	s_add_i32 s33, 0, 0x20600
	s_mov_b32 s1, 0
	s_branch .LBB0_228

; __device__ __forceinline__ int mk_lane() { int l = (int)__builtin_amdgcn_mbcnt_hi(~0u, __builtin_amdgcn_mbcnt_lo(~0u, 0u)); asm volatile("" : "+v"(l)); return l; }
; #define LAS __attribute__((address_space(3)))
; #define PH(k) (IN(k) && ((MK_MASK >> (k)) & 1))
; #define REPS(k) for (int rep_ = 0; rep_ < (((MK_REP_MASK) >> (k)) & 1) + 1; ++rep_)
; template <class Sched> __device__ __forceinline__ void build_rstd_tables(LAS unsigned char* lds, const Sched& S, const float* sspart, float eps, int wave) {
;     const int lane = mk_lane(), tid = wave * 64 + lane;
;     LAS int* pml = (LAS int*)(lds + RING_BYTES + 1536); LAS float* tab = (LAS float*)(lds + RING_BYTES + 2048);
;     if (tid == 0) { int n = 0; pg8::Unit u; for (int i = 0; S.next(i, u); ++i) { bool f = false; for (int j = 0; j < n; ++j) f |= (pml[j] == u.pm); if (!f && n < 8) pml[n++] = u.pm; } pml[8] = n; }
;     __syncthreads();
;     const int n = pml[8];
; __global__ void __launch_bounds__(NWAVES * 64, 2) mk_fwd(Params P) {
;     ...
;     if (PH(5)) REPS(5) { pg8::Gemm g{H1B, Wcq_t, M, D, D}; pg8::StaticOrder S; S.init(M, D, G, bx);
;         build_rstd_tables(lds, S, SS1, EPS, wave);
;         pg8::EpiRowScale<0> E{CQ, D, SS1, EPS, pg8::CROSS_C2, (const LAS int*)(lds + RING_BYTES + 1536), (const LAS float*)(lds + RING_BYTES + 2048)};
.LBB0_991:
	s_cmp_lt_i32 s74, 6
	s_cselect_b64 s[0:1], -1, 0
	s_and_b64 s[36:37], s[0:1], s[4:5]
	s_andn2_b64 vcc, exec, s[36:37]
	s_cbranch_vccnz .LBB0_1089
	v_and_b32_e32 v248, 15, v212
	v_lshrrev_b32_e32 v249, 2, v212
	v_sub_u32_e32 v249, v249, v248
	v_lshrrev_b32_e32 v248, 4, v212
	v_and_b32_e32 v253, 3, v212
	v_sub_u32_e32 v248, v253, v248
	v_lshlrev_b32_e32 v248, 4, v248
	v_mul_i32_i24_e32 v250, 0x800, v249
	v_add_u32_e32 v250, v250, v248
	v_ashrrev_i32_e32 v251, 31, v250
	v_lshlrev_b32_e32 v253, 4, v253
	v_lshrrev_b32_e32 v248, 2, v212
	v_add_u32_e32 v253, v253, v248
	v_lshlrev_b32_e32 v253, 2, v253
	s_and_b32 s20, s93, 0xffffffc0
	v_mov_b32_e32 v3, v212
	s_ashr_i32 s2, s82, 31
	v_add_u32_e32 v2, s20, v3
	s_ashr_i32 s3, s88, 31
	s_mov_b32 s21, 0
	v_cmp_eq_u32_e32 vcc, 0, v2
	s_and_saveexec_b64 s[38:39], vcc
	s_cbranch_execz .LBB0_1018
	s_waitcnt lgkmcnt(0)
	s_cmp_lg_u32 s82, 0x100
	s_cbranch_scc1 .Lmy_pmlgen_p1
	s_and_b32 s33, s88, 7
	s_lshl_b32 s33, s33, 4
	s_bfe_u32 s1, s88, 0x30003
	s_add_i32 s33, s33, s1
	v_mov_b32_e32 v0, 0x20600
	v_mov_b32_e32 v1, s33
	ds_write_b32 v0, v1
	v_add_u32_e32 v1, 8, v1
	ds_write_b32 v0, v1 offset:4
	v_mov_b32_e32 v1, 2
	ds_write_b32 v0, v1 offset:32
	s_branch .LBB0_1018
.Lmy_pmlgen_p1:
	v_mov_b64_e32 v[0:1], 0x1ff
	s_add_i32 s33, 0, 0x20600
	s_mov_b32 s1, 0
	s_branch .LBB0_996

; __device__ __forceinline__ int mk_lane() { int l = (int)__builtin_amdgcn_mbcnt_hi(~0u, __builtin_amdgcn_mbcnt_lo(~0u, 0u)); asm volatile("" : "+v"(l)); return l; }
; #define LAS __attribute__((address_space(3)))
; #define PH(k) (IN(k) && ((MK_MASK >> (k)) & 1))
; #define REPS(k) for (int rep_ = 0; rep_ < (((MK_REP_MASK) >> (k)) & 1) + 1; ++rep_)
; template <class Sched> __device__ __forceinline__ void build_rstd_tables(LAS unsigned char* lds, const Sched& S, const float* sspart, float eps, int wave) {
;     const int lane = mk_lane(), tid = wave * 64 + lane;
;     LAS int* pml = (LAS int*)(lds + RING_BYTES + 1536); LAS float* tab = (LAS float*)(lds + RING_BYTES + 2048);
;     if (tid == 0) { int n = 0; pg8::Unit u; for (int i = 0; S.next(i, u); ++i) { bool f = false; for (int j = 0; j < n; ++j) f |= (pml[j] == u.pm); if (!f && n < 8) pml[n++] = u.pm; } pml[8] = n; }
;     __syncthreads();
;     const int n = pml[8];
; __global__ void __launch_bounds__(NWAVES * 64, 2) mk_fwd(Params P) {
;     ...
;     if (PH(8)) REPS(8) { pg8::Gemm g{H2B, Wup_t, M, FF, D}; pg8::StaticOrder S; S.init(M, FF, G, bx);
;         build_rstd_tables(lds, S, SS2, EPS, wave);
;         pg8::EpiRowScale<1> E{ZH, FF, SS2, EPS, 1.f, (const LAS int*)(lds + RING_BYTES + 1536), (const LAS float*)(lds + RING_BYTES + 2048)};
.LBB0_1290:
	s_cmp_lt_i32 s74, 9
	s_cselect_b64 s[0:1], -1, 0
	s_and_b64 s[36:37], s[0:1], s[4:5]
	s_andn2_b64 vcc, exec, s[36:37]
	s_cbranch_vccnz .LBB0_1388
	v_and_b32_e32 v248, 15, v212
	v_lshrrev_b32_e32 v249, 2, v212
	v_sub_u32_e32 v249, v249, v248
	v_lshrrev_b32_e32 v248, 4, v212
	v_and_b32_e32 v253, 3, v212
	v_sub_u32_e32 v248, v253, v248
	v_lshlrev_b32_e32 v248, 4, v248
	v_mul_i32_i24_e32 v250, 0x2000, v249
	v_add_u32_e32 v250, v250, v248
	v_ashrrev_i32_e32 v251, 31, v250
	v_lshlrev_b32_e32 v253, 4, v253
	v_lshrrev_b32_e32 v248, 2, v212
	v_add_u32_e32 v253, v253, v248
	v_lshlrev_b32_e32 v253, 2, v253
	s_and_b32 s20, s93, 0xffffffc0
	v_mov_b32_e32 v3, v212
	s_ashr_i32 s2, s82, 31
	v_add_u32_e32 v2, s20, v3
	s_ashr_i32 s3, s88, 31
	s_mov_b32 s21, 0
	v_cmp_eq_u32_e32 vcc, 0, v2
	s_and_saveexec_b64 s[38:39], vcc
	s_cbranch_execz .LBB0_1317
	s_waitcnt lgkmcnt(0)
	s_cmp_lg_u32 s82, 0x100
	s_cbranch_scc1 .Lmy_pmlgen_p0
	s_and_b32 s33, s88, 7
	s_lshl_b32 s33, s33, 4
	s_bfe_u32 s1, s88, 0x30003
	s_add_i32 s33, s33, s1
	v_mov_b32_e32 v0, 0x20600
	v_mov_b32_e32 v1, s33
	ds_write_b32 v0, v1
	v_add_u32_e32 v1, 8, v1
	ds_write_b32 v0, v1 offset:4
	v_mov_b32_e32 v1, 2
	ds_write_b32 v0, v1 offset:32
	s_branch .LBB0_1317
.Lmy_pmlgen_p0:
	v_mov_b64_e32 v[0:1], 0x7ff
	s_add_i32 s33, 0, 0x20600
	s_mov_b32 s1, 0
	s_branch .LBB0_1295
